# acc_zeroing_mov_b64
# speedup vs baseline: 1.1093x; 1.0073x over previous
.LBB0_149:
	s_ashr_i32 s13, s12, 31
	v_cmp_lt_i64_e32 vcc, s[14:15], v[140:141]
	s_lshl_b64 s[14:15], s[12:13], 19
	s_add_u32 s14, s90, s14
	s_addc_u32 s15, s91, s15
	s_and_b64 s[34:35], vcc, exec
	s_cselect_b32 s13, s15, s39
	s_cselect_b32 s37, s14, s38
	s_ashr_i32 s9, s8, 31
	s_lshl_b64 s[34:35], s[8:9], 19
	s_add_u32 s34, s30, s34
	s_addc_u32 s35, s31, s35
	s_and_b64 s[42:43], vcc, exec
	s_cselect_b32 s9, s35, s41
	s_cselect_b32 s72, s34, s40
	s_add_u32 s38, s38, 0x40080
	s_addc_u32 s39, s39, 0
	s_add_u32 s73, s40, 0x100
	v_mov_b32_e32 v0, 0
	s_addc_u32 s74, s41, 0
	s_mov_b32 s75, -2
	v_mov_b32_e32 v1, v0
	v_mov_b64_e32 v[2:3], v[0:1]
	v_mov_b64_e32 v[4:5], v[0:1]
	v_mov_b64_e32 v[6:7], v[0:1]
	v_mov_b64_e32 v[8:9], v[0:1]
	v_mov_b64_e32 v[10:11], v[0:1]
	v_mov_b64_e32 v[12:13], v[0:1]
	v_mov_b64_e32 v[14:15], v[0:1]
	v_mov_b64_e32 v[16:17], v[0:1]
	v_mov_b64_e32 v[18:19], v[0:1]
	v_mov_b64_e32 v[20:21], v[0:1]
	v_mov_b64_e32 v[22:23], v[0:1]
	v_mov_b64_e32 v[24:25], v[0:1]
	v_mov_b64_e32 v[26:27], v[0:1]
	v_mov_b64_e32 v[28:29], v[0:1]
	v_mov_b64_e32 v[30:31], v[0:1]
	v_mov_b64_e32 v[32:33], v[0:1]
	v_mov_b64_e32 v[34:35], v[0:1]
	v_mov_b64_e32 v[36:37], v[0:1]
	v_mov_b64_e32 v[38:39], v[0:1]
	v_mov_b64_e32 v[40:41], v[0:1]
	v_mov_b64_e32 v[42:43], v[0:1]
	v_mov_b64_e32 v[44:45], v[0:1]
	v_mov_b64_e32 v[46:47], v[0:1]
	v_mov_b64_e32 v[48:49], v[0:1]
	v_mov_b64_e32 v[50:51], v[0:1]
	v_mov_b64_e32 v[52:53], v[0:1]
	v_mov_b64_e32 v[54:55], v[0:1]
	v_mov_b64_e32 v[56:57], v[0:1]
	v_mov_b64_e32 v[58:59], v[0:1]
	v_mov_b64_e32 v[60:61], v[0:1]
	v_mov_b64_e32 v[62:63], v[0:1]
	v_mov_b64_e32 v[64:65], v[0:1]
	v_mov_b64_e32 v[66:67], v[0:1]
	v_mov_b64_e32 v[68:69], v[0:1]
	v_mov_b64_e32 v[70:71], v[0:1]
	v_mov_b64_e32 v[72:73], v[0:1]
	v_mov_b64_e32 v[74:75], v[0:1]
	v_mov_b64_e32 v[76:77], v[0:1]
	v_mov_b64_e32 v[78:79], v[0:1]
	v_mov_b64_e32 v[80:81], v[0:1]
	v_mov_b64_e32 v[82:83], v[0:1]
	v_mov_b64_e32 v[84:85], v[0:1]
	v_mov_b64_e32 v[86:87], v[0:1]
	v_mov_b64_e32 v[88:89], v[0:1]
	v_mov_b64_e32 v[90:91], v[0:1]
	v_mov_b64_e32 v[92:93], v[0:1]
	v_mov_b64_e32 v[94:95], v[0:1]
	v_mov_b64_e32 v[96:97], v[0:1]
	v_mov_b64_e32 v[98:99], v[0:1]
	v_mov_b64_e32 v[100:101], v[0:1]
	v_mov_b64_e32 v[102:103], v[0:1]
	v_mov_b64_e32 v[104:105], v[0:1]
	v_mov_b64_e32 v[106:107], v[0:1]
	v_mov_b64_e32 v[108:109], v[0:1]
	v_mov_b64_e32 v[110:111], v[0:1]
	v_mov_b64_e32 v[112:113], v[0:1]
	v_mov_b64_e32 v[114:115], v[0:1]
	v_mov_b64_e32 v[116:117], v[0:1]
	v_mov_b64_e32 v[118:119], v[0:1]
	v_mov_b64_e32 v[120:121], v[0:1]
	v_mov_b64_e32 v[122:123], v[0:1]
	v_mov_b64_e32 v[124:125], v[0:1]
	v_mov_b64_e32 v[126:127], v[0:1]

.LBB0_176:
	s_ashr_i32 s9, s8, 31
	v_cmp_lt_i64_e32 vcc, s[14:15], v[140:141]
	s_lshl_b64 s[14:15], s[8:9], 19
	s_add_u32 s14, s28, s14
	s_addc_u32 s15, s29, s15
	s_and_b64 s[30:31], vcc, exec
	s_cselect_b32 s9, s15, s35
	s_cselect_b32 s64, s14, s34
	s_ashr_i32 s3, s2, 31
	s_lshl_b64 s[30:31], s[2:3], 19
	s_add_u32 s30, s90, s30
	s_addc_u32 s31, s91, s31
	s_and_b64 s[38:39], vcc, exec
	s_cselect_b32 s3, s31, s37
	s_cselect_b32 s65, s30, s36
	s_add_u32 s34, s34, 0x40080
	s_addc_u32 s35, s35, 0
	s_add_u32 s66, s36, 0x100
	v_mov_b32_e32 v0, 0
	s_addc_u32 s67, s37, 0
	s_mov_b32 s68, -2
	v_mov_b32_e32 v1, v0
	v_mov_b64_e32 v[2:3], v[0:1]
	v_mov_b64_e32 v[4:5], v[0:1]
	v_mov_b64_e32 v[6:7], v[0:1]
	v_mov_b64_e32 v[8:9], v[0:1]
	v_mov_b64_e32 v[10:11], v[0:1]
	v_mov_b64_e32 v[12:13], v[0:1]
	v_mov_b64_e32 v[14:15], v[0:1]
	v_mov_b64_e32 v[16:17], v[0:1]
	v_mov_b64_e32 v[18:19], v[0:1]
	v_mov_b64_e32 v[20:21], v[0:1]
	v_mov_b64_e32 v[22:23], v[0:1]
	v_mov_b64_e32 v[24:25], v[0:1]
	v_mov_b64_e32 v[26:27], v[0:1]
	v_mov_b64_e32 v[28:29], v[0:1]
	v_mov_b64_e32 v[30:31], v[0:1]
	v_mov_b64_e32 v[32:33], v[0:1]
	v_mov_b64_e32 v[34:35], v[0:1]
	v_mov_b64_e32 v[36:37], v[0:1]
	v_mov_b64_e32 v[38:39], v[0:1]
	v_mov_b64_e32 v[40:41], v[0:1]
	v_mov_b64_e32 v[42:43], v[0:1]
	v_mov_b64_e32 v[44:45], v[0:1]
	v_mov_b64_e32 v[46:47], v[0:1]
	v_mov_b64_e32 v[48:49], v[0:1]
	v_mov_b64_e32 v[50:51], v[0:1]
	v_mov_b64_e32 v[52:53], v[0:1]
	v_mov_b64_e32 v[54:55], v[0:1]
	v_mov_b64_e32 v[56:57], v[0:1]
	v_mov_b64_e32 v[58:59], v[0:1]
	v_mov_b64_e32 v[60:61], v[0:1]
	v_mov_b64_e32 v[62:63], v[0:1]
	v_mov_b64_e32 v[64:65], v[0:1]
	v_mov_b64_e32 v[66:67], v[0:1]
	v_mov_b64_e32 v[68:69], v[0:1]
	v_mov_b64_e32 v[70:71], v[0:1]
	v_mov_b64_e32 v[72:73], v[0:1]
	v_mov_b64_e32 v[74:75], v[0:1]
	v_mov_b64_e32 v[76:77], v[0:1]
	v_mov_b64_e32 v[78:79], v[0:1]
	v_mov_b64_e32 v[80:81], v[0:1]
	v_mov_b64_e32 v[82:83], v[0:1]
	v_mov_b64_e32 v[84:85], v[0:1]
	v_mov_b64_e32 v[86:87], v[0:1]
	v_mov_b64_e32 v[88:89], v[0:1]
	v_mov_b64_e32 v[90:91], v[0:1]
	v_mov_b64_e32 v[92:93], v[0:1]
	v_mov_b64_e32 v[94:95], v[0:1]
	v_mov_b64_e32 v[96:97], v[0:1]
	v_mov_b64_e32 v[98:99], v[0:1]
	v_mov_b64_e32 v[100:101], v[0:1]
	v_mov_b64_e32 v[102:103], v[0:1]
	v_mov_b64_e32 v[104:105], v[0:1]
	v_mov_b64_e32 v[106:107], v[0:1]
	v_mov_b64_e32 v[108:109], v[0:1]
	v_mov_b64_e32 v[110:111], v[0:1]
	v_mov_b64_e32 v[112:113], v[0:1]
	v_mov_b64_e32 v[114:115], v[0:1]
	v_mov_b64_e32 v[116:117], v[0:1]
	v_mov_b64_e32 v[118:119], v[0:1]
	v_mov_b64_e32 v[120:121], v[0:1]
	v_mov_b64_e32 v[122:123], v[0:1]
	v_mov_b64_e32 v[124:125], v[0:1]
	v_mov_b64_e32 v[126:127], v[0:1]

.LBB0_199:
	s_ashr_i32 s35, s34, 31
	v_cmp_lt_i64_e64 s[50:51], s[38:39], 32
	s_lshl_b64 s[38:39], s[34:35], 19
	s_add_u32 s38, s54, s38
	s_addc_u32 s39, s55, s39
	s_and_b64 s[40:41], s[50:51], exec
	s_cselect_b32 s35, s39, s43
	s_cselect_b32 s76, s38, s42
	s_ashr_i32 s31, s30, 31
	s_lshl_b64 s[40:41], s[30:31], 19
	s_add_u32 s40, s67, s40
	s_addc_u32 s41, s68, s41
	s_and_b64 s[50:51], s[50:51], exec
	s_cselect_b32 s31, s41, s49
	s_cselect_b32 s77, s40, s48
	s_add_u32 s42, s42, 0x40080
	s_addc_u32 s43, s43, 0
	s_add_u32 s78, s48, 0x100
	v_mov_b32_e32 v0, 0
	s_addc_u32 s79, s49, 0
	s_mov_b32 s80, -2
	v_mov_b32_e32 v1, v0
	v_mov_b64_e32 v[2:3], v[0:1]
	v_mov_b64_e32 v[4:5], v[0:1]
	v_mov_b64_e32 v[6:7], v[0:1]
	v_mov_b64_e32 v[8:9], v[0:1]
	v_mov_b64_e32 v[10:11], v[0:1]
	v_mov_b64_e32 v[12:13], v[0:1]
	v_mov_b64_e32 v[14:15], v[0:1]
	v_mov_b64_e32 v[16:17], v[0:1]
	v_mov_b64_e32 v[18:19], v[0:1]
	v_mov_b64_e32 v[20:21], v[0:1]
	v_mov_b64_e32 v[22:23], v[0:1]
	v_mov_b64_e32 v[24:25], v[0:1]
	v_mov_b64_e32 v[26:27], v[0:1]
	v_mov_b64_e32 v[28:29], v[0:1]
	v_mov_b64_e32 v[30:31], v[0:1]
	v_mov_b64_e32 v[32:33], v[0:1]
	v_mov_b64_e32 v[34:35], v[0:1]
	v_mov_b64_e32 v[36:37], v[0:1]
	v_mov_b64_e32 v[38:39], v[0:1]
	v_mov_b64_e32 v[40:41], v[0:1]
	v_mov_b64_e32 v[42:43], v[0:1]
	v_mov_b64_e32 v[44:45], v[0:1]
	v_mov_b64_e32 v[46:47], v[0:1]
	v_mov_b64_e32 v[48:49], v[0:1]
	v_mov_b64_e32 v[50:51], v[0:1]
	v_mov_b64_e32 v[52:53], v[0:1]
	v_mov_b64_e32 v[54:55], v[0:1]
	v_mov_b64_e32 v[56:57], v[0:1]
	v_mov_b64_e32 v[58:59], v[0:1]
	v_mov_b64_e32 v[60:61], v[0:1]
	v_mov_b64_e32 v[62:63], v[0:1]
	v_mov_b64_e32 v[64:65], v[0:1]
	v_mov_b64_e32 v[66:67], v[0:1]
	v_mov_b64_e32 v[68:69], v[0:1]
	v_mov_b64_e32 v[70:71], v[0:1]
	v_mov_b64_e32 v[72:73], v[0:1]
	v_mov_b64_e32 v[74:75], v[0:1]
	v_mov_b64_e32 v[76:77], v[0:1]
	v_mov_b64_e32 v[78:79], v[0:1]
	v_mov_b64_e32 v[80:81], v[0:1]
	v_mov_b64_e32 v[82:83], v[0:1]
	v_mov_b64_e32 v[84:85], v[0:1]
	v_mov_b64_e32 v[86:87], v[0:1]
	v_mov_b64_e32 v[88:89], v[0:1]
	v_mov_b64_e32 v[90:91], v[0:1]
	v_mov_b64_e32 v[92:93], v[0:1]
	v_mov_b64_e32 v[94:95], v[0:1]
	v_mov_b64_e32 v[96:97], v[0:1]
	v_mov_b64_e32 v[98:99], v[0:1]
	v_mov_b64_e32 v[100:101], v[0:1]
	v_mov_b64_e32 v[102:103], v[0:1]
	v_mov_b64_e32 v[104:105], v[0:1]
	v_mov_b64_e32 v[106:107], v[0:1]
	v_mov_b64_e32 v[108:109], v[0:1]
	v_mov_b64_e32 v[110:111], v[0:1]
	v_mov_b64_e32 v[112:113], v[0:1]
	v_mov_b64_e32 v[114:115], v[0:1]
	v_mov_b64_e32 v[116:117], v[0:1]
	v_mov_b64_e32 v[118:119], v[0:1]
	v_mov_b64_e32 v[120:121], v[0:1]
	v_mov_b64_e32 v[122:123], v[0:1]
	v_mov_b64_e32 v[124:125], v[0:1]
	v_mov_b64_e32 v[126:127], v[0:1]

.LBB0_219:
	s_ashr_i32 s29, s28, 31
	v_cmp_lt_i64_e64 s[42:43], s[34:35], 32
	s_lshl_b64 s[34:35], s[28:29], 19
	s_add_u32 s34, s51, s34
	s_addc_u32 s35, s63, s35
	s_and_b64 s[36:37], s[42:43], exec
	s_cselect_b32 s29, s35, s39
	s_cselect_b32 s71, s34, s38
	s_ashr_i32 s15, s14, 31
	s_lshl_b64 s[36:37], s[14:15], 19
	s_add_u32 s36, s54, s36
	s_addc_u32 s37, s55, s37
	s_and_b64 s[42:43], s[42:43], exec
	s_cselect_b32 s15, s37, s41
	s_cselect_b32 s72, s36, s40
	s_add_u32 s38, s38, 0x40080
	s_addc_u32 s39, s39, 0
	s_add_u32 s73, s40, 0x100
	v_mov_b32_e32 v0, 0
	s_addc_u32 s74, s41, 0
	s_mov_b32 s75, -2
	v_mov_b32_e32 v1, v0
	v_mov_b64_e32 v[2:3], v[0:1]
	v_mov_b64_e32 v[4:5], v[0:1]
	v_mov_b64_e32 v[6:7], v[0:1]
	v_mov_b64_e32 v[8:9], v[0:1]
	v_mov_b64_e32 v[10:11], v[0:1]
	v_mov_b64_e32 v[12:13], v[0:1]
	v_mov_b64_e32 v[14:15], v[0:1]
	v_mov_b64_e32 v[16:17], v[0:1]
	v_mov_b64_e32 v[18:19], v[0:1]
	v_mov_b64_e32 v[20:21], v[0:1]
	v_mov_b64_e32 v[22:23], v[0:1]
	v_mov_b64_e32 v[24:25], v[0:1]
	v_mov_b64_e32 v[26:27], v[0:1]
	v_mov_b64_e32 v[28:29], v[0:1]
	v_mov_b64_e32 v[30:31], v[0:1]
	v_mov_b64_e32 v[32:33], v[0:1]
	v_mov_b64_e32 v[34:35], v[0:1]
	v_mov_b64_e32 v[36:37], v[0:1]
	v_mov_b64_e32 v[38:39], v[0:1]
	v_mov_b64_e32 v[40:41], v[0:1]
	v_mov_b64_e32 v[42:43], v[0:1]
	v_mov_b64_e32 v[44:45], v[0:1]
	v_mov_b64_e32 v[46:47], v[0:1]
	v_mov_b64_e32 v[48:49], v[0:1]
	v_mov_b64_e32 v[50:51], v[0:1]
	v_mov_b64_e32 v[52:53], v[0:1]
	v_mov_b64_e32 v[54:55], v[0:1]
	v_mov_b64_e32 v[56:57], v[0:1]
	v_mov_b64_e32 v[58:59], v[0:1]
	v_mov_b64_e32 v[60:61], v[0:1]
	v_mov_b64_e32 v[62:63], v[0:1]
	v_mov_b64_e32 v[64:65], v[0:1]
	v_mov_b64_e32 v[66:67], v[0:1]
	v_mov_b64_e32 v[68:69], v[0:1]
	v_mov_b64_e32 v[70:71], v[0:1]
	v_mov_b64_e32 v[72:73], v[0:1]
	v_mov_b64_e32 v[74:75], v[0:1]
	v_mov_b64_e32 v[76:77], v[0:1]
	v_mov_b64_e32 v[78:79], v[0:1]
	v_mov_b64_e32 v[80:81], v[0:1]
	v_mov_b64_e32 v[82:83], v[0:1]
	v_mov_b64_e32 v[84:85], v[0:1]
	v_mov_b64_e32 v[86:87], v[0:1]
	v_mov_b64_e32 v[88:89], v[0:1]
	v_mov_b64_e32 v[90:91], v[0:1]
	v_mov_b64_e32 v[92:93], v[0:1]
	v_mov_b64_e32 v[94:95], v[0:1]
	v_mov_b64_e32 v[96:97], v[0:1]
	v_mov_b64_e32 v[98:99], v[0:1]
	v_mov_b64_e32 v[100:101], v[0:1]
	v_mov_b64_e32 v[102:103], v[0:1]
	v_mov_b64_e32 v[104:105], v[0:1]
	v_mov_b64_e32 v[106:107], v[0:1]
	v_mov_b64_e32 v[108:109], v[0:1]
	v_mov_b64_e32 v[110:111], v[0:1]
	v_mov_b64_e32 v[112:113], v[0:1]
	v_mov_b64_e32 v[114:115], v[0:1]
	v_mov_b64_e32 v[116:117], v[0:1]
	v_mov_b64_e32 v[118:119], v[0:1]
	v_mov_b64_e32 v[120:121], v[0:1]
	v_mov_b64_e32 v[122:123], v[0:1]
	v_mov_b64_e32 v[124:125], v[0:1]
	v_mov_b64_e32 v[126:127], v[0:1]

.LBB0_653:
	s_ashr_i32 s13, s12, 31
	v_cmp_lt_i64_e32 vcc, s[14:15], v[140:141]
	s_lshl_b64 s[14:15], s[12:13], 19
	s_add_u32 s14, s90, s14
	s_addc_u32 s15, s91, s15
	s_and_b64 s[16:17], vcc, exec
	s_cselect_b32 s13, s15, s23
	s_cselect_b32 s19, s14, s22
	s_ashr_i32 s3, s2, 31
	s_lshl_b64 s[16:17], s[2:3], 19
	v_readlane_b32 s26, v253, 55
	v_readlane_b32 s27, v253, 56
	s_add_u32 s16, s26, s16
	s_addc_u32 s17, s27, s17
	s_and_b64 s[26:27], vcc, exec
	s_cselect_b32 s3, s17, s25
	s_cselect_b32 s42, s16, s24
	s_add_u32 s22, s22, 0x40080
	s_addc_u32 s23, s23, 0
	s_add_u32 s43, s24, 0x100
	v_mov_b32_e32 v0, 0
	s_addc_u32 s48, s25, 0
	s_mov_b32 s49, -2
	s_waitcnt lgkmcnt(0)
	v_mov_b32_e32 v1, v0
	v_mov_b64_e32 v[2:3], v[0:1]
	v_mov_b64_e32 v[4:5], v[0:1]
	v_mov_b64_e32 v[6:7], v[0:1]
	v_mov_b64_e32 v[8:9], v[0:1]
	v_mov_b64_e32 v[10:11], v[0:1]
	v_mov_b64_e32 v[12:13], v[0:1]
	v_mov_b64_e32 v[14:15], v[0:1]
	v_mov_b64_e32 v[16:17], v[0:1]
	v_mov_b64_e32 v[18:19], v[0:1]
	v_mov_b64_e32 v[20:21], v[0:1]
	v_mov_b64_e32 v[22:23], v[0:1]
	v_mov_b64_e32 v[24:25], v[0:1]
	v_mov_b64_e32 v[26:27], v[0:1]
	v_mov_b64_e32 v[28:29], v[0:1]
	v_mov_b64_e32 v[30:31], v[0:1]
	v_mov_b64_e32 v[32:33], v[0:1]
	v_mov_b64_e32 v[34:35], v[0:1]
	v_mov_b64_e32 v[36:37], v[0:1]
	v_mov_b64_e32 v[38:39], v[0:1]
	v_mov_b64_e32 v[40:41], v[0:1]
	v_mov_b64_e32 v[42:43], v[0:1]
	v_mov_b64_e32 v[44:45], v[0:1]
	v_mov_b64_e32 v[46:47], v[0:1]
	v_mov_b64_e32 v[48:49], v[0:1]
	v_mov_b64_e32 v[50:51], v[0:1]
	v_mov_b64_e32 v[52:53], v[0:1]
	v_mov_b64_e32 v[54:55], v[0:1]
	v_mov_b64_e32 v[56:57], v[0:1]
	v_mov_b64_e32 v[58:59], v[0:1]
	v_mov_b64_e32 v[60:61], v[0:1]
	v_mov_b64_e32 v[62:63], v[0:1]
	v_mov_b64_e32 v[64:65], v[0:1]
	v_mov_b64_e32 v[66:67], v[0:1]
	v_mov_b64_e32 v[68:69], v[0:1]
	v_mov_b64_e32 v[70:71], v[0:1]
	v_mov_b64_e32 v[72:73], v[0:1]
	v_mov_b64_e32 v[74:75], v[0:1]
	v_mov_b64_e32 v[76:77], v[0:1]
	v_mov_b64_e32 v[78:79], v[0:1]
	v_mov_b64_e32 v[80:81], v[0:1]
	v_mov_b64_e32 v[82:83], v[0:1]
	v_mov_b64_e32 v[84:85], v[0:1]
	v_mov_b64_e32 v[86:87], v[0:1]
	v_mov_b64_e32 v[88:89], v[0:1]
	v_mov_b64_e32 v[90:91], v[0:1]
	v_mov_b64_e32 v[92:93], v[0:1]
	v_mov_b64_e32 v[94:95], v[0:1]
	v_mov_b64_e32 v[96:97], v[0:1]
	v_mov_b64_e32 v[98:99], v[0:1]
	v_mov_b64_e32 v[100:101], v[0:1]
	v_mov_b64_e32 v[102:103], v[0:1]
	v_mov_b64_e32 v[104:105], v[0:1]
	v_mov_b64_e32 v[106:107], v[0:1]
	v_mov_b64_e32 v[108:109], v[0:1]
	v_mov_b64_e32 v[110:111], v[0:1]
	v_mov_b64_e32 v[112:113], v[0:1]
	v_mov_b64_e32 v[114:115], v[0:1]
	v_mov_b64_e32 v[116:117], v[0:1]
	v_mov_b64_e32 v[118:119], v[0:1]
	v_mov_b64_e32 v[120:121], v[0:1]
	v_mov_b64_e32 v[122:123], v[0:1]
	v_mov_b64_e32 v[124:125], v[0:1]
	v_mov_b64_e32 v[126:127], v[0:1]

.LBB0_711:
	s_ashr_i32 s21, s20, 31
	v_cmp_lt_i64_e32 vcc, s[22:23], v[140:141]
	s_lshl_b64 s[22:23], s[20:21], 19
	s_add_u32 s22, s10, s22
	s_addc_u32 s23, s11, s23
	s_and_b64 s[24:25], vcc, exec
	s_cselect_b32 s21, s23, s3
	s_cselect_b32 s52, s22, s2
	s_ashr_i32 s19, s18, 31
	s_lshl_b64 s[24:25], s[18:19], 19
	v_readlane_b32 s19, v253, 49
	s_add_u32 s24, s19, s24
	v_readlane_b32 s19, v253, 50
	s_addc_u32 s25, s19, s25
	s_and_b64 s[28:29], vcc, exec
	s_cselect_b32 s19, s25, s27
	s_cselect_b32 s53, s24, s26
	s_add_u32 s2, s2, 0x40080
	s_addc_u32 s3, s3, 0
	s_add_u32 s54, s26, 0x100
	v_mov_b32_e32 v0, 0
	s_addc_u32 s55, s27, 0
	s_mov_b32 s56, -2
	v_mov_b32_e32 v1, v0
	v_mov_b64_e32 v[2:3], v[0:1]
	v_mov_b64_e32 v[4:5], v[0:1]
	v_mov_b64_e32 v[6:7], v[0:1]
	v_mov_b64_e32 v[8:9], v[0:1]
	v_mov_b64_e32 v[10:11], v[0:1]
	v_mov_b64_e32 v[12:13], v[0:1]
	v_mov_b64_e32 v[14:15], v[0:1]
	v_mov_b64_e32 v[16:17], v[0:1]
	v_mov_b64_e32 v[18:19], v[0:1]
	v_mov_b64_e32 v[20:21], v[0:1]
	v_mov_b64_e32 v[22:23], v[0:1]
	v_mov_b64_e32 v[24:25], v[0:1]
	v_mov_b64_e32 v[26:27], v[0:1]
	v_mov_b64_e32 v[28:29], v[0:1]
	v_mov_b64_e32 v[30:31], v[0:1]
	v_mov_b64_e32 v[32:33], v[0:1]
	v_mov_b64_e32 v[34:35], v[0:1]
	v_mov_b64_e32 v[36:37], v[0:1]
	v_mov_b64_e32 v[38:39], v[0:1]
	v_mov_b64_e32 v[40:41], v[0:1]
	v_mov_b64_e32 v[42:43], v[0:1]
	v_mov_b64_e32 v[44:45], v[0:1]
	v_mov_b64_e32 v[46:47], v[0:1]
	v_mov_b64_e32 v[48:49], v[0:1]
	v_mov_b64_e32 v[50:51], v[0:1]
	v_mov_b64_e32 v[52:53], v[0:1]
	v_mov_b64_e32 v[54:55], v[0:1]
	v_mov_b64_e32 v[56:57], v[0:1]
	v_mov_b64_e32 v[58:59], v[0:1]
	v_mov_b64_e32 v[60:61], v[0:1]
	v_mov_b64_e32 v[62:63], v[0:1]
	v_mov_b64_e32 v[64:65], v[0:1]
	v_mov_b64_e32 v[66:67], v[0:1]
	v_mov_b64_e32 v[68:69], v[0:1]
	v_mov_b64_e32 v[70:71], v[0:1]
	v_mov_b64_e32 v[72:73], v[0:1]
	v_mov_b64_e32 v[74:75], v[0:1]
	v_mov_b64_e32 v[76:77], v[0:1]
	v_mov_b64_e32 v[78:79], v[0:1]
	v_mov_b64_e32 v[80:81], v[0:1]
	v_mov_b64_e32 v[82:83], v[0:1]
	v_mov_b64_e32 v[84:85], v[0:1]
	v_mov_b64_e32 v[86:87], v[0:1]
	v_mov_b64_e32 v[88:89], v[0:1]
	v_mov_b64_e32 v[90:91], v[0:1]
	v_mov_b64_e32 v[92:93], v[0:1]
	v_mov_b64_e32 v[94:95], v[0:1]
	v_mov_b64_e32 v[96:97], v[0:1]
	v_mov_b64_e32 v[98:99], v[0:1]
	v_mov_b64_e32 v[100:101], v[0:1]
	v_mov_b64_e32 v[102:103], v[0:1]
	v_mov_b64_e32 v[104:105], v[0:1]
	v_mov_b64_e32 v[106:107], v[0:1]
	v_mov_b64_e32 v[108:109], v[0:1]
	v_mov_b64_e32 v[110:111], v[0:1]
	v_mov_b64_e32 v[112:113], v[0:1]
	v_mov_b64_e32 v[114:115], v[0:1]
	v_mov_b64_e32 v[116:117], v[0:1]
	v_mov_b64_e32 v[118:119], v[0:1]
	v_mov_b64_e32 v[120:121], v[0:1]
	v_mov_b64_e32 v[122:123], v[0:1]
	v_mov_b64_e32 v[124:125], v[0:1]
	v_mov_b64_e32 v[126:127], v[0:1]

.LBB0_791:
	s_ashr_i32 s27, s26, 31
	v_cmp_lt_i64_e32 vcc, s[28:29], v[140:141]
	s_lshl_b64 s[28:29], s[26:27], 18
	s_add_u32 s28, s71, s28
	s_addc_u32 s29, s72, s29
	s_and_b64 s[30:31], vcc, exec
	s_cselect_b32 s27, s29, s39
	s_cselect_b32 s35, s28, s38
	s_ashr_i32 s25, s24, 31
	s_lshl_b64 s[30:31], s[24:25], 18
	v_readlane_b32 s25, v253, 47
	s_add_u32 s30, s25, s30
	v_readlane_b32 s25, v253, 48
	s_addc_u32 s31, s25, s31
	s_and_b64 s[42:43], vcc, exec
	s_cselect_b32 s25, s31, s41
	s_cselect_b32 s60, s30, s40
	s_add_u32 s38, s38, 0x20080
	s_addc_u32 s39, s39, 0
	s_add_u32 s61, s40, 0x100
	v_mov_b32_e32 v0, 0
	s_addc_u32 s62, s41, 0
	s_mov_b32 s63, -2
	s_waitcnt lgkmcnt(0)
	v_mov_b32_e32 v1, v0
	v_mov_b64_e32 v[2:3], v[0:1]
	v_mov_b64_e32 v[4:5], v[0:1]
	v_mov_b64_e32 v[6:7], v[0:1]
	v_mov_b64_e32 v[8:9], v[0:1]
	v_mov_b64_e32 v[10:11], v[0:1]
	v_mov_b64_e32 v[12:13], v[0:1]
	v_mov_b64_e32 v[14:15], v[0:1]
	v_mov_b64_e32 v[16:17], v[0:1]
	v_mov_b64_e32 v[18:19], v[0:1]
	v_mov_b64_e32 v[20:21], v[0:1]
	v_mov_b64_e32 v[22:23], v[0:1]
	v_mov_b64_e32 v[24:25], v[0:1]
	v_mov_b64_e32 v[26:27], v[0:1]
	v_mov_b64_e32 v[28:29], v[0:1]
	v_mov_b64_e32 v[30:31], v[0:1]
	v_mov_b64_e32 v[32:33], v[0:1]
	v_mov_b64_e32 v[34:35], v[0:1]
	v_mov_b64_e32 v[36:37], v[0:1]
	v_mov_b64_e32 v[38:39], v[0:1]
	v_mov_b64_e32 v[40:41], v[0:1]
	v_mov_b64_e32 v[42:43], v[0:1]
	v_mov_b64_e32 v[44:45], v[0:1]
	v_mov_b64_e32 v[46:47], v[0:1]
	v_mov_b64_e32 v[48:49], v[0:1]
	v_mov_b64_e32 v[50:51], v[0:1]
	v_mov_b64_e32 v[52:53], v[0:1]
	v_mov_b64_e32 v[54:55], v[0:1]
	v_mov_b64_e32 v[56:57], v[0:1]
	v_mov_b64_e32 v[58:59], v[0:1]
	v_mov_b64_e32 v[60:61], v[0:1]
	v_mov_b64_e32 v[62:63], v[0:1]
	v_mov_b64_e32 v[64:65], v[0:1]
	v_mov_b64_e32 v[66:67], v[0:1]
	v_mov_b64_e32 v[68:69], v[0:1]
	v_mov_b64_e32 v[70:71], v[0:1]
	v_mov_b64_e32 v[72:73], v[0:1]
	v_mov_b64_e32 v[74:75], v[0:1]
	v_mov_b64_e32 v[76:77], v[0:1]
	v_mov_b64_e32 v[78:79], v[0:1]
	v_mov_b64_e32 v[80:81], v[0:1]
	v_mov_b64_e32 v[82:83], v[0:1]
	v_mov_b64_e32 v[84:85], v[0:1]
	v_mov_b64_e32 v[86:87], v[0:1]
	v_mov_b64_e32 v[88:89], v[0:1]
	v_mov_b64_e32 v[90:91], v[0:1]
	v_mov_b64_e32 v[92:93], v[0:1]
	v_mov_b64_e32 v[94:95], v[0:1]
	v_mov_b64_e32 v[96:97], v[0:1]
	v_mov_b64_e32 v[98:99], v[0:1]
	v_mov_b64_e32 v[100:101], v[0:1]
	v_mov_b64_e32 v[102:103], v[0:1]
	v_mov_b64_e32 v[104:105], v[0:1]
	v_mov_b64_e32 v[106:107], v[0:1]
	v_mov_b64_e32 v[108:109], v[0:1]
	v_mov_b64_e32 v[110:111], v[0:1]
	v_mov_b64_e32 v[112:113], v[0:1]
	v_mov_b64_e32 v[114:115], v[0:1]
	v_mov_b64_e32 v[116:117], v[0:1]
	v_mov_b64_e32 v[118:119], v[0:1]
	v_mov_b64_e32 v[120:121], v[0:1]
	v_mov_b64_e32 v[122:123], v[0:1]
	v_mov_b64_e32 v[124:125], v[0:1]
	v_mov_b64_e32 v[126:127], v[0:1]

.LBB0_849:
	s_ashr_i32 s27, s26, 31
	v_cmp_lt_i64_e32 vcc, s[28:29], v[140:141]
	s_lshl_b64 s[28:29], s[26:27], 19
	s_add_u32 s28, s90, s28
	s_addc_u32 s29, s91, s29
	s_and_b64 s[30:31], vcc, exec
	s_cselect_b32 s27, s29, s35
	s_cselect_b32 s62, s28, s34
	s_ashr_i32 s25, s24, 31
	s_lshl_b64 s[30:31], s[24:25], 19
	v_readlane_b32 s25, v253, 45
	s_add_u32 s30, s25, s30
	v_readlane_b32 s25, v253, 46
	s_addc_u32 s31, s25, s31
	s_and_b64 s[38:39], vcc, exec
	s_cselect_b32 s25, s31, s37
	s_cselect_b32 s63, s30, s36
	s_add_u32 s34, s34, 0x40080
	s_addc_u32 s35, s35, 0
	s_add_u32 s64, s36, 0x100
	v_mov_b32_e32 v0, 0
	s_addc_u32 s65, s37, 0
	s_mov_b32 s66, -2
	v_mov_b32_e32 v1, v0
	v_mov_b64_e32 v[2:3], v[0:1]
	v_mov_b64_e32 v[4:5], v[0:1]
	v_mov_b64_e32 v[6:7], v[0:1]
	v_mov_b64_e32 v[8:9], v[0:1]
	v_mov_b64_e32 v[10:11], v[0:1]
	v_mov_b64_e32 v[12:13], v[0:1]
	v_mov_b64_e32 v[14:15], v[0:1]
	v_mov_b64_e32 v[16:17], v[0:1]
	v_mov_b64_e32 v[18:19], v[0:1]
	v_mov_b64_e32 v[20:21], v[0:1]
	v_mov_b64_e32 v[22:23], v[0:1]
	v_mov_b64_e32 v[24:25], v[0:1]
	v_mov_b64_e32 v[26:27], v[0:1]
	v_mov_b64_e32 v[28:29], v[0:1]
	v_mov_b64_e32 v[30:31], v[0:1]
	v_mov_b64_e32 v[32:33], v[0:1]
	v_mov_b64_e32 v[34:35], v[0:1]
	v_mov_b64_e32 v[36:37], v[0:1]
	v_mov_b64_e32 v[38:39], v[0:1]
	v_mov_b64_e32 v[40:41], v[0:1]
	v_mov_b64_e32 v[42:43], v[0:1]
	v_mov_b64_e32 v[44:45], v[0:1]
	v_mov_b64_e32 v[46:47], v[0:1]
	v_mov_b64_e32 v[48:49], v[0:1]
	v_mov_b64_e32 v[50:51], v[0:1]
	v_mov_b64_e32 v[52:53], v[0:1]
	v_mov_b64_e32 v[54:55], v[0:1]
	v_mov_b64_e32 v[56:57], v[0:1]
	v_mov_b64_e32 v[58:59], v[0:1]
	v_mov_b64_e32 v[60:61], v[0:1]
	v_mov_b64_e32 v[62:63], v[0:1]
	v_mov_b64_e32 v[64:65], v[0:1]
	v_mov_b64_e32 v[66:67], v[0:1]
	v_mov_b64_e32 v[68:69], v[0:1]
	v_mov_b64_e32 v[70:71], v[0:1]
	v_mov_b64_e32 v[72:73], v[0:1]
	v_mov_b64_e32 v[74:75], v[0:1]
	v_mov_b64_e32 v[76:77], v[0:1]
	v_mov_b64_e32 v[78:79], v[0:1]
	v_mov_b64_e32 v[80:81], v[0:1]
	v_mov_b64_e32 v[82:83], v[0:1]
	v_mov_b64_e32 v[84:85], v[0:1]
	v_mov_b64_e32 v[86:87], v[0:1]
	v_mov_b64_e32 v[88:89], v[0:1]
	v_mov_b64_e32 v[90:91], v[0:1]
	v_mov_b64_e32 v[92:93], v[0:1]
	v_mov_b64_e32 v[94:95], v[0:1]
	v_mov_b64_e32 v[96:97], v[0:1]
	v_mov_b64_e32 v[98:99], v[0:1]
	v_mov_b64_e32 v[100:101], v[0:1]
	v_mov_b64_e32 v[102:103], v[0:1]
	v_mov_b64_e32 v[104:105], v[0:1]
	v_mov_b64_e32 v[106:107], v[0:1]
	v_mov_b64_e32 v[108:109], v[0:1]
	v_mov_b64_e32 v[110:111], v[0:1]
	v_mov_b64_e32 v[112:113], v[0:1]
	v_mov_b64_e32 v[114:115], v[0:1]
	v_mov_b64_e32 v[116:117], v[0:1]
	v_mov_b64_e32 v[118:119], v[0:1]
	v_mov_b64_e32 v[120:121], v[0:1]
	v_mov_b64_e32 v[122:123], v[0:1]
	v_mov_b64_e32 v[124:125], v[0:1]
	v_mov_b64_e32 v[126:127], v[0:1]

.LBB0_895:
	s_ashr_i32 s29, s28, 31
	v_cmp_lt_i64_e32 vcc, s[30:31], v[140:141]
	s_lshl_b64 s[30:31], s[28:29], 21
	s_add_u32 s30, s92, s30
	s_addc_u32 s31, s93, s31
	s_and_b64 s[34:35], vcc, exec
	s_cselect_b32 s29, s31, s41
	s_cselect_b32 s37, s30, s40
	s_ashr_i32 s27, s26, 31
	s_lshl_b64 s[34:35], s[26:27], 21
	v_readlane_b32 s27, v253, 57
	s_add_u32 s34, s27, s34
	v_readlane_b32 s27, v253, 58
	s_addc_u32 s35, s27, s35
	s_and_b64 s[48:49], vcc, exec
	s_cselect_b32 s27, s35, s43
	s_cselect_b32 s62, s34, s42
	s_add_u32 s40, s40, 0x100080
	s_addc_u32 s41, s41, 0
	s_add_u32 s63, s42, 0x100
	v_mov_b32_e32 v0, 0
	s_addc_u32 s64, s43, 0
	s_mov_b32 s65, -2
	s_waitcnt lgkmcnt(0)
	v_mov_b32_e32 v1, v0
	v_mov_b64_e32 v[2:3], v[0:1]
	v_mov_b64_e32 v[4:5], v[0:1]
	v_mov_b64_e32 v[6:7], v[0:1]
	v_mov_b64_e32 v[8:9], v[0:1]
	v_mov_b64_e32 v[10:11], v[0:1]
	v_mov_b64_e32 v[12:13], v[0:1]
	v_mov_b64_e32 v[14:15], v[0:1]
	v_mov_b64_e32 v[16:17], v[0:1]
	v_mov_b64_e32 v[18:19], v[0:1]
	v_mov_b64_e32 v[20:21], v[0:1]
	v_mov_b64_e32 v[22:23], v[0:1]
	v_mov_b64_e32 v[24:25], v[0:1]
	v_mov_b64_e32 v[26:27], v[0:1]
	v_mov_b64_e32 v[28:29], v[0:1]
	v_mov_b64_e32 v[30:31], v[0:1]
	v_mov_b64_e32 v[32:33], v[0:1]
	v_mov_b64_e32 v[34:35], v[0:1]
	v_mov_b64_e32 v[36:37], v[0:1]
	v_mov_b64_e32 v[38:39], v[0:1]
	v_mov_b64_e32 v[40:41], v[0:1]
	v_mov_b64_e32 v[42:43], v[0:1]
	v_mov_b64_e32 v[44:45], v[0:1]
	v_mov_b64_e32 v[46:47], v[0:1]
	v_mov_b64_e32 v[48:49], v[0:1]
	v_mov_b64_e32 v[50:51], v[0:1]
	v_mov_b64_e32 v[52:53], v[0:1]
	v_mov_b64_e32 v[54:55], v[0:1]
	v_mov_b64_e32 v[56:57], v[0:1]
	v_mov_b64_e32 v[58:59], v[0:1]
	v_mov_b64_e32 v[60:61], v[0:1]
	v_mov_b64_e32 v[62:63], v[0:1]
	v_mov_b64_e32 v[64:65], v[0:1]
	v_mov_b64_e32 v[66:67], v[0:1]
	v_mov_b64_e32 v[68:69], v[0:1]
	v_mov_b64_e32 v[70:71], v[0:1]
	v_mov_b64_e32 v[72:73], v[0:1]
	v_mov_b64_e32 v[74:75], v[0:1]
	v_mov_b64_e32 v[76:77], v[0:1]
	v_mov_b64_e32 v[78:79], v[0:1]
	v_mov_b64_e32 v[80:81], v[0:1]
	v_mov_b64_e32 v[82:83], v[0:1]
	v_mov_b64_e32 v[84:85], v[0:1]
	v_mov_b64_e32 v[86:87], v[0:1]
	v_mov_b64_e32 v[88:89], v[0:1]
	v_mov_b64_e32 v[90:91], v[0:1]
	v_mov_b64_e32 v[92:93], v[0:1]
	v_mov_b64_e32 v[94:95], v[0:1]
	v_mov_b64_e32 v[96:97], v[0:1]
	v_mov_b64_e32 v[98:99], v[0:1]
	v_mov_b64_e32 v[100:101], v[0:1]
	v_mov_b64_e32 v[102:103], v[0:1]
	v_mov_b64_e32 v[104:105], v[0:1]
	v_mov_b64_e32 v[106:107], v[0:1]
	v_mov_b64_e32 v[108:109], v[0:1]
	v_mov_b64_e32 v[110:111], v[0:1]
	v_mov_b64_e32 v[112:113], v[0:1]
	v_mov_b64_e32 v[114:115], v[0:1]
	v_mov_b64_e32 v[116:117], v[0:1]
	v_mov_b64_e32 v[118:119], v[0:1]
	v_mov_b64_e32 v[120:121], v[0:1]
	v_mov_b64_e32 v[122:123], v[0:1]
	v_mov_b64_e32 v[124:125], v[0:1]
	v_mov_b64_e32 v[126:127], v[0:1]

.LBB0_945:
	s_ashr_i32 s23, s22, 31
	v_cmp_lt_i64_e32 vcc, s[24:25], v[140:141]
	s_lshl_b64 s[24:25], s[22:23], 19
	s_add_u32 s24, s10, s24
	s_addc_u32 s25, s11, s25
	s_and_b64 s[26:27], vcc, exec
	s_cselect_b32 s23, s25, s3
	s_cselect_b32 s54, s24, s2
	s_ashr_i32 s21, s20, 31
	s_lshl_b64 s[26:27], s[20:21], 19
	v_readlane_b32 s30, v253, 53
	v_readlane_b32 s31, v253, 54
	s_add_u32 s26, s30, s26
	s_addc_u32 s27, s31, s27
	s_and_b64 s[30:31], vcc, exec
	s_cselect_b32 s21, s27, s29
	s_cselect_b32 s55, s26, s28
	s_add_u32 s2, s2, 0x40080
	s_addc_u32 s3, s3, 0
	s_add_u32 s56, s28, 0x100
	v_mov_b32_e32 v0, 0
	s_addc_u32 s57, s29, 0
	s_mov_b32 s58, -2
	v_mov_b32_e32 v1, v0
	v_mov_b64_e32 v[2:3], v[0:1]
	v_mov_b64_e32 v[4:5], v[0:1]
	v_mov_b64_e32 v[6:7], v[0:1]
	v_mov_b64_e32 v[8:9], v[0:1]
	v_mov_b64_e32 v[10:11], v[0:1]
	v_mov_b64_e32 v[12:13], v[0:1]
	v_mov_b64_e32 v[14:15], v[0:1]
	v_mov_b64_e32 v[16:17], v[0:1]
	v_mov_b64_e32 v[18:19], v[0:1]
	v_mov_b64_e32 v[20:21], v[0:1]
	v_mov_b64_e32 v[22:23], v[0:1]
	v_mov_b64_e32 v[24:25], v[0:1]
	v_mov_b64_e32 v[26:27], v[0:1]
	v_mov_b64_e32 v[28:29], v[0:1]
	v_mov_b64_e32 v[30:31], v[0:1]
	v_mov_b64_e32 v[32:33], v[0:1]
	v_mov_b64_e32 v[34:35], v[0:1]
	v_mov_b64_e32 v[36:37], v[0:1]
	v_mov_b64_e32 v[38:39], v[0:1]
	v_mov_b64_e32 v[40:41], v[0:1]
	v_mov_b64_e32 v[42:43], v[0:1]
	v_mov_b64_e32 v[44:45], v[0:1]
	v_mov_b64_e32 v[46:47], v[0:1]
	v_mov_b64_e32 v[48:49], v[0:1]
	v_mov_b64_e32 v[50:51], v[0:1]
	v_mov_b64_e32 v[52:53], v[0:1]
	v_mov_b64_e32 v[54:55], v[0:1]
	v_mov_b64_e32 v[56:57], v[0:1]
	v_mov_b64_e32 v[58:59], v[0:1]
	v_mov_b64_e32 v[60:61], v[0:1]
	v_mov_b64_e32 v[62:63], v[0:1]
	v_mov_b64_e32 v[64:65], v[0:1]
	v_mov_b64_e32 v[66:67], v[0:1]
	v_mov_b64_e32 v[68:69], v[0:1]
	v_mov_b64_e32 v[70:71], v[0:1]
	v_mov_b64_e32 v[72:73], v[0:1]
	v_mov_b64_e32 v[74:75], v[0:1]
	v_mov_b64_e32 v[76:77], v[0:1]
	v_mov_b64_e32 v[78:79], v[0:1]
	v_mov_b64_e32 v[80:81], v[0:1]
	v_mov_b64_e32 v[82:83], v[0:1]
	v_mov_b64_e32 v[84:85], v[0:1]
	v_mov_b64_e32 v[86:87], v[0:1]
	v_mov_b64_e32 v[88:89], v[0:1]
	v_mov_b64_e32 v[90:91], v[0:1]
	v_mov_b64_e32 v[92:93], v[0:1]
	v_mov_b64_e32 v[94:95], v[0:1]
	v_mov_b64_e32 v[96:97], v[0:1]
	v_mov_b64_e32 v[98:99], v[0:1]
	v_mov_b64_e32 v[100:101], v[0:1]
	v_mov_b64_e32 v[102:103], v[0:1]
	v_mov_b64_e32 v[104:105], v[0:1]
	v_mov_b64_e32 v[106:107], v[0:1]
	v_mov_b64_e32 v[108:109], v[0:1]
	v_mov_b64_e32 v[110:111], v[0:1]
	v_mov_b64_e32 v[112:113], v[0:1]
	v_mov_b64_e32 v[114:115], v[0:1]
	v_mov_b64_e32 v[116:117], v[0:1]
	v_mov_b64_e32 v[118:119], v[0:1]
	v_mov_b64_e32 v[120:121], v[0:1]
	v_mov_b64_e32 v[122:123], v[0:1]
	v_mov_b64_e32 v[124:125], v[0:1]
	v_mov_b64_e32 v[126:127], v[0:1]

.LBB0_1021:
	s_ashr_i32 s29, s28, 31
	v_cmp_lt_i64_e32 vcc, s[30:31], v[140:141]
	s_lshl_b64 s[30:31], s[28:29], 19
	s_add_u32 s30, s90, s30
	s_addc_u32 s31, s91, s31
	s_and_b64 s[34:35], vcc, exec
	s_cselect_b32 s29, s31, s41
	s_cselect_b32 s37, s30, s40
	s_ashr_i32 s27, s26, 31
	s_lshl_b64 s[34:35], s[26:27], 19
	v_readlane_b32 s48, v253, 51
	v_readlane_b32 s49, v253, 52
	s_add_u32 s34, s48, s34
	s_addc_u32 s35, s49, s35
	s_and_b64 s[48:49], vcc, exec
	s_cselect_b32 s27, s35, s43
	s_cselect_b32 s61, s34, s42
	s_add_u32 s40, s40, 0x40080
	s_addc_u32 s41, s41, 0
	s_add_u32 s62, s42, 0x100
	v_mov_b32_e32 v0, 0
	s_addc_u32 s63, s43, 0
	s_mov_b32 s64, -2
	s_waitcnt lgkmcnt(0)
	v_mov_b32_e32 v1, v0
	v_mov_b64_e32 v[2:3], v[0:1]
	v_mov_b64_e32 v[4:5], v[0:1]
	v_mov_b64_e32 v[6:7], v[0:1]
	v_mov_b64_e32 v[8:9], v[0:1]
	v_mov_b64_e32 v[10:11], v[0:1]
	v_mov_b64_e32 v[12:13], v[0:1]
	v_mov_b64_e32 v[14:15], v[0:1]
	v_mov_b64_e32 v[16:17], v[0:1]
	v_mov_b64_e32 v[18:19], v[0:1]
	v_mov_b64_e32 v[20:21], v[0:1]
	v_mov_b64_e32 v[22:23], v[0:1]
	v_mov_b64_e32 v[24:25], v[0:1]
	v_mov_b64_e32 v[26:27], v[0:1]
	v_mov_b64_e32 v[28:29], v[0:1]
	v_mov_b64_e32 v[30:31], v[0:1]
	v_mov_b64_e32 v[32:33], v[0:1]
	v_mov_b64_e32 v[34:35], v[0:1]
	v_mov_b64_e32 v[36:37], v[0:1]
	v_mov_b64_e32 v[38:39], v[0:1]
	v_mov_b64_e32 v[40:41], v[0:1]
	v_mov_b64_e32 v[42:43], v[0:1]
	v_mov_b64_e32 v[44:45], v[0:1]
	v_mov_b64_e32 v[46:47], v[0:1]
	v_mov_b64_e32 v[48:49], v[0:1]
	v_mov_b64_e32 v[50:51], v[0:1]
	v_mov_b64_e32 v[52:53], v[0:1]
	v_mov_b64_e32 v[54:55], v[0:1]
	v_mov_b64_e32 v[56:57], v[0:1]
	v_mov_b64_e32 v[58:59], v[0:1]
	v_mov_b64_e32 v[60:61], v[0:1]
	v_mov_b64_e32 v[62:63], v[0:1]
	v_mov_b64_e32 v[64:65], v[0:1]
	v_mov_b64_e32 v[66:67], v[0:1]
	v_mov_b64_e32 v[68:69], v[0:1]
	v_mov_b64_e32 v[70:71], v[0:1]
	v_mov_b64_e32 v[72:73], v[0:1]
	v_mov_b64_e32 v[74:75], v[0:1]
	v_mov_b64_e32 v[76:77], v[0:1]
	v_mov_b64_e32 v[78:79], v[0:1]
	v_mov_b64_e32 v[80:81], v[0:1]
	v_mov_b64_e32 v[82:83], v[0:1]
	v_mov_b64_e32 v[84:85], v[0:1]
	v_mov_b64_e32 v[86:87], v[0:1]
	v_mov_b64_e32 v[88:89], v[0:1]
	v_mov_b64_e32 v[90:91], v[0:1]
	v_mov_b64_e32 v[92:93], v[0:1]
	v_mov_b64_e32 v[94:95], v[0:1]
	v_mov_b64_e32 v[96:97], v[0:1]
	v_mov_b64_e32 v[98:99], v[0:1]
	v_mov_b64_e32 v[100:101], v[0:1]
	v_mov_b64_e32 v[102:103], v[0:1]
	v_mov_b64_e32 v[104:105], v[0:1]
	v_mov_b64_e32 v[106:107], v[0:1]
	v_mov_b64_e32 v[108:109], v[0:1]
	v_mov_b64_e32 v[110:111], v[0:1]
	v_mov_b64_e32 v[112:113], v[0:1]
	v_mov_b64_e32 v[114:115], v[0:1]
	v_mov_b64_e32 v[116:117], v[0:1]
	v_mov_b64_e32 v[118:119], v[0:1]
	v_mov_b64_e32 v[120:121], v[0:1]
	v_mov_b64_e32 v[122:123], v[0:1]
	v_mov_b64_e32 v[124:125], v[0:1]
	v_mov_b64_e32 v[126:127], v[0:1]

.LBB0_1079:
	s_ashr_i32 s29, s28, 31
	v_cmp_lt_i64_e32 vcc, s[30:31], v[140:141]
	s_lshl_b64 s[30:31], s[28:29], 19
	s_add_u32 s30, s10, s30
	s_addc_u32 s31, s11, s31
	s_and_b64 s[34:35], vcc, exec
	s_cselect_b32 s29, s31, s3
	s_cselect_b32 s63, s30, s2
	s_ashr_i32 s27, s26, 31
	s_lshl_b64 s[34:35], s[26:27], 19
	s_add_u32 s34, s41, s34
	s_addc_u32 s35, s42, s35
	s_and_b64 s[38:39], vcc, exec
	s_cselect_b32 s27, s35, s37
	s_cselect_b32 s64, s34, s36
	s_add_u32 s2, s2, 0x40080
	s_addc_u32 s3, s3, 0
	s_add_u32 s65, s36, 0x100
	v_mov_b32_e32 v0, 0
	s_addc_u32 s66, s37, 0
	s_mov_b32 s67, -2
	v_mov_b32_e32 v1, v0
	v_mov_b64_e32 v[2:3], v[0:1]
	v_mov_b64_e32 v[4:5], v[0:1]
	v_mov_b64_e32 v[6:7], v[0:1]
	v_mov_b64_e32 v[8:9], v[0:1]
	v_mov_b64_e32 v[10:11], v[0:1]
	v_mov_b64_e32 v[12:13], v[0:1]
	v_mov_b64_e32 v[14:15], v[0:1]
	v_mov_b64_e32 v[16:17], v[0:1]
	v_mov_b64_e32 v[18:19], v[0:1]
	v_mov_b64_e32 v[20:21], v[0:1]
	v_mov_b64_e32 v[22:23], v[0:1]
	v_mov_b64_e32 v[24:25], v[0:1]
	v_mov_b64_e32 v[26:27], v[0:1]
	v_mov_b64_e32 v[28:29], v[0:1]
	v_mov_b64_e32 v[30:31], v[0:1]
	v_mov_b64_e32 v[32:33], v[0:1]
	v_mov_b64_e32 v[34:35], v[0:1]
	v_mov_b64_e32 v[36:37], v[0:1]
	v_mov_b64_e32 v[38:39], v[0:1]
	v_mov_b64_e32 v[40:41], v[0:1]
	v_mov_b64_e32 v[42:43], v[0:1]
	v_mov_b64_e32 v[44:45], v[0:1]
	v_mov_b64_e32 v[46:47], v[0:1]
	v_mov_b64_e32 v[48:49], v[0:1]
	v_mov_b64_e32 v[50:51], v[0:1]
	v_mov_b64_e32 v[52:53], v[0:1]
	v_mov_b64_e32 v[54:55], v[0:1]
	v_mov_b64_e32 v[56:57], v[0:1]
	v_mov_b64_e32 v[58:59], v[0:1]
	v_mov_b64_e32 v[60:61], v[0:1]
	v_mov_b64_e32 v[62:63], v[0:1]
	v_mov_b64_e32 v[64:65], v[0:1]
	v_mov_b64_e32 v[66:67], v[0:1]
	v_mov_b64_e32 v[68:69], v[0:1]
	v_mov_b64_e32 v[70:71], v[0:1]
	v_mov_b64_e32 v[72:73], v[0:1]
	v_mov_b64_e32 v[74:75], v[0:1]
	v_mov_b64_e32 v[76:77], v[0:1]
	v_mov_b64_e32 v[78:79], v[0:1]
	v_mov_b64_e32 v[80:81], v[0:1]
	v_mov_b64_e32 v[82:83], v[0:1]
	v_mov_b64_e32 v[84:85], v[0:1]
	v_mov_b64_e32 v[86:87], v[0:1]
	v_mov_b64_e32 v[88:89], v[0:1]
	v_mov_b64_e32 v[90:91], v[0:1]
	v_mov_b64_e32 v[92:93], v[0:1]
	v_mov_b64_e32 v[94:95], v[0:1]
	v_mov_b64_e32 v[96:97], v[0:1]
	v_mov_b64_e32 v[98:99], v[0:1]
	v_mov_b64_e32 v[100:101], v[0:1]
	v_mov_b64_e32 v[102:103], v[0:1]
	v_mov_b64_e32 v[104:105], v[0:1]
	v_mov_b64_e32 v[106:107], v[0:1]
	v_mov_b64_e32 v[108:109], v[0:1]
	v_mov_b64_e32 v[110:111], v[0:1]
	v_mov_b64_e32 v[112:113], v[0:1]
	v_mov_b64_e32 v[114:115], v[0:1]
	v_mov_b64_e32 v[116:117], v[0:1]
	v_mov_b64_e32 v[118:119], v[0:1]
	v_mov_b64_e32 v[120:121], v[0:1]
	v_mov_b64_e32 v[122:123], v[0:1]
	v_mov_b64_e32 v[124:125], v[0:1]
	v_mov_b64_e32 v[126:127], v[0:1]

.LBB0_1159:
	s_ashr_i32 s25, s24, 31
	v_cmp_lt_i64_e32 vcc, s[26:27], v[140:141]
	s_lshl_b64 s[26:27], s[24:25], 18
	s_add_u32 s26, s71, s26
	s_addc_u32 s27, s72, s27
	s_and_b64 s[28:29], vcc, exec
	s_cselect_b32 s25, s27, s37
	s_cselect_b32 s31, s26, s36
	s_ashr_i32 s23, s22, 31
	s_lshl_b64 s[28:29], s[22:23], 18
	s_add_u32 s28, s42, s28
	s_addc_u32 s29, s43, s29
	s_and_b64 s[40:41], vcc, exec
	s_cselect_b32 s23, s29, s39
	s_cselect_b32 s59, s28, s38
	s_add_u32 s36, s36, 0x20080
	s_addc_u32 s37, s37, 0
	s_add_u32 s60, s38, 0x100
	v_mov_b32_e32 v0, 0
	s_addc_u32 s61, s39, 0
	s_mov_b32 s62, -2
	s_waitcnt lgkmcnt(0)
	v_mov_b32_e32 v1, v0
	v_mov_b64_e32 v[2:3], v[0:1]
	v_mov_b64_e32 v[4:5], v[0:1]
	v_mov_b64_e32 v[6:7], v[0:1]
	v_mov_b64_e32 v[8:9], v[0:1]
	v_mov_b64_e32 v[10:11], v[0:1]
	v_mov_b64_e32 v[12:13], v[0:1]
	v_mov_b64_e32 v[14:15], v[0:1]
	v_mov_b64_e32 v[16:17], v[0:1]
	v_mov_b64_e32 v[18:19], v[0:1]
	v_mov_b64_e32 v[20:21], v[0:1]
	v_mov_b64_e32 v[22:23], v[0:1]
	v_mov_b64_e32 v[24:25], v[0:1]
	v_mov_b64_e32 v[26:27], v[0:1]
	v_mov_b64_e32 v[28:29], v[0:1]
	v_mov_b64_e32 v[30:31], v[0:1]
	v_mov_b64_e32 v[32:33], v[0:1]
	v_mov_b64_e32 v[34:35], v[0:1]
	v_mov_b64_e32 v[36:37], v[0:1]
	v_mov_b64_e32 v[38:39], v[0:1]
	v_mov_b64_e32 v[40:41], v[0:1]
	v_mov_b64_e32 v[42:43], v[0:1]
	v_mov_b64_e32 v[44:45], v[0:1]
	v_mov_b64_e32 v[46:47], v[0:1]
	v_mov_b64_e32 v[48:49], v[0:1]
	v_mov_b64_e32 v[50:51], v[0:1]
	v_mov_b64_e32 v[52:53], v[0:1]
	v_mov_b64_e32 v[54:55], v[0:1]
	v_mov_b64_e32 v[56:57], v[0:1]
	v_mov_b64_e32 v[58:59], v[0:1]
	v_mov_b64_e32 v[60:61], v[0:1]
	v_mov_b64_e32 v[62:63], v[0:1]
	v_mov_b64_e32 v[64:65], v[0:1]
	v_mov_b64_e32 v[66:67], v[0:1]
	v_mov_b64_e32 v[68:69], v[0:1]
	v_mov_b64_e32 v[70:71], v[0:1]
	v_mov_b64_e32 v[72:73], v[0:1]
	v_mov_b64_e32 v[74:75], v[0:1]
	v_mov_b64_e32 v[76:77], v[0:1]
	v_mov_b64_e32 v[78:79], v[0:1]
	v_mov_b64_e32 v[80:81], v[0:1]
	v_mov_b64_e32 v[82:83], v[0:1]
	v_mov_b64_e32 v[84:85], v[0:1]
	v_mov_b64_e32 v[86:87], v[0:1]
	v_mov_b64_e32 v[88:89], v[0:1]
	v_mov_b64_e32 v[90:91], v[0:1]
	v_mov_b64_e32 v[92:93], v[0:1]
	v_mov_b64_e32 v[94:95], v[0:1]
	v_mov_b64_e32 v[96:97], v[0:1]
	v_mov_b64_e32 v[98:99], v[0:1]
	v_mov_b64_e32 v[100:101], v[0:1]
	v_mov_b64_e32 v[102:103], v[0:1]
	v_mov_b64_e32 v[104:105], v[0:1]
	v_mov_b64_e32 v[106:107], v[0:1]
	v_mov_b64_e32 v[108:109], v[0:1]
	v_mov_b64_e32 v[110:111], v[0:1]
	v_mov_b64_e32 v[112:113], v[0:1]
	v_mov_b64_e32 v[114:115], v[0:1]
	v_mov_b64_e32 v[116:117], v[0:1]
	v_mov_b64_e32 v[118:119], v[0:1]
	v_mov_b64_e32 v[120:121], v[0:1]
	v_mov_b64_e32 v[122:123], v[0:1]
	v_mov_b64_e32 v[124:125], v[0:1]
	v_mov_b64_e32 v[126:127], v[0:1]

.LBB0_1217:
	s_ashr_i32 s23, s22, 31
	v_cmp_lt_i64_e32 vcc, s[24:25], v[140:141]
	s_lshl_b64 s[24:25], s[22:23], 19
	s_add_u32 s24, s90, s24
	s_addc_u32 s25, s91, s25
	s_and_b64 s[26:27], vcc, exec
	s_cselect_b32 s23, s25, s29
	s_cselect_b32 s59, s24, s28
	s_ashr_i32 s21, s20, 31
	s_lshl_b64 s[26:27], s[20:21], 19
	s_add_u32 s26, s37, s26
	s_addc_u32 s27, s38, s27
	s_and_b64 s[34:35], vcc, exec
	s_cselect_b32 s21, s27, s31
	s_cselect_b32 s60, s26, s30
	s_add_u32 s28, s28, 0x40080
	s_addc_u32 s29, s29, 0
	s_add_u32 s61, s30, 0x100
	v_mov_b32_e32 v0, 0
	s_addc_u32 s62, s31, 0
	s_mov_b32 s63, -2
	v_mov_b32_e32 v1, v0
	v_mov_b64_e32 v[2:3], v[0:1]
	v_mov_b64_e32 v[4:5], v[0:1]
	v_mov_b64_e32 v[6:7], v[0:1]
	v_mov_b64_e32 v[8:9], v[0:1]
	v_mov_b64_e32 v[10:11], v[0:1]
	v_mov_b64_e32 v[12:13], v[0:1]
	v_mov_b64_e32 v[14:15], v[0:1]
	v_mov_b64_e32 v[16:17], v[0:1]
	v_mov_b64_e32 v[18:19], v[0:1]
	v_mov_b64_e32 v[20:21], v[0:1]
	v_mov_b64_e32 v[22:23], v[0:1]
	v_mov_b64_e32 v[24:25], v[0:1]
	v_mov_b64_e32 v[26:27], v[0:1]
	v_mov_b64_e32 v[28:29], v[0:1]
	v_mov_b64_e32 v[30:31], v[0:1]
	v_mov_b64_e32 v[32:33], v[0:1]
	v_mov_b64_e32 v[34:35], v[0:1]
	v_mov_b64_e32 v[36:37], v[0:1]
	v_mov_b64_e32 v[38:39], v[0:1]
	v_mov_b64_e32 v[40:41], v[0:1]
	v_mov_b64_e32 v[42:43], v[0:1]
	v_mov_b64_e32 v[44:45], v[0:1]
	v_mov_b64_e32 v[46:47], v[0:1]
	v_mov_b64_e32 v[48:49], v[0:1]
	v_mov_b64_e32 v[50:51], v[0:1]
	v_mov_b64_e32 v[52:53], v[0:1]
	v_mov_b64_e32 v[54:55], v[0:1]
	v_mov_b64_e32 v[56:57], v[0:1]
	v_mov_b64_e32 v[58:59], v[0:1]
	v_mov_b64_e32 v[60:61], v[0:1]
	v_mov_b64_e32 v[62:63], v[0:1]
	v_mov_b64_e32 v[64:65], v[0:1]
	v_mov_b64_e32 v[66:67], v[0:1]
	v_mov_b64_e32 v[68:69], v[0:1]
	v_mov_b64_e32 v[70:71], v[0:1]
	v_mov_b64_e32 v[72:73], v[0:1]
	v_mov_b64_e32 v[74:75], v[0:1]
	v_mov_b64_e32 v[76:77], v[0:1]
	v_mov_b64_e32 v[78:79], v[0:1]
	v_mov_b64_e32 v[80:81], v[0:1]
	v_mov_b64_e32 v[82:83], v[0:1]
	v_mov_b64_e32 v[84:85], v[0:1]
	v_mov_b64_e32 v[86:87], v[0:1]
	v_mov_b64_e32 v[88:89], v[0:1]
	v_mov_b64_e32 v[90:91], v[0:1]
	v_mov_b64_e32 v[92:93], v[0:1]
	v_mov_b64_e32 v[94:95], v[0:1]
	v_mov_b64_e32 v[96:97], v[0:1]
	v_mov_b64_e32 v[98:99], v[0:1]
	v_mov_b64_e32 v[100:101], v[0:1]
	v_mov_b64_e32 v[102:103], v[0:1]
	v_mov_b64_e32 v[104:105], v[0:1]
	v_mov_b64_e32 v[106:107], v[0:1]
	v_mov_b64_e32 v[108:109], v[0:1]
	v_mov_b64_e32 v[110:111], v[0:1]
	v_mov_b64_e32 v[112:113], v[0:1]
	v_mov_b64_e32 v[114:115], v[0:1]
	v_mov_b64_e32 v[116:117], v[0:1]
	v_mov_b64_e32 v[118:119], v[0:1]
	v_mov_b64_e32 v[120:121], v[0:1]
	v_mov_b64_e32 v[122:123], v[0:1]
	v_mov_b64_e32 v[124:125], v[0:1]
	v_mov_b64_e32 v[126:127], v[0:1]

.LBB0_1263:
	s_ashr_i32 s21, s20, 31
	v_cmp_lt_i64_e32 vcc, s[22:23], v[140:141]
	s_lshl_b64 s[22:23], s[20:21], 21
	s_add_u32 s22, s92, s22
	s_addc_u32 s23, s93, s23
	s_and_b64 s[24:25], vcc, exec
	s_cselect_b32 s21, s23, s31
	s_cselect_b32 s27, s22, s30
	s_ashr_i32 s19, s18, 31
	s_lshl_b64 s[24:25], s[18:19], 21
	s_add_u32 s24, s38, s24
	s_addc_u32 s25, s39, s25
	s_and_b64 s[36:37], vcc, exec
	s_cselect_b32 s19, s25, s35
	s_cselect_b32 s55, s24, s34
	s_add_u32 s30, s30, 0x100080
	s_addc_u32 s31, s31, 0
	s_add_u32 s56, s34, 0x100
	v_mov_b32_e32 v0, 0
	s_addc_u32 s57, s35, 0
	s_mov_b32 s58, -2
	s_waitcnt lgkmcnt(0)
	v_mov_b32_e32 v1, v0
	v_mov_b64_e32 v[2:3], v[0:1]
	v_mov_b64_e32 v[4:5], v[0:1]
	v_mov_b64_e32 v[6:7], v[0:1]
	v_mov_b64_e32 v[8:9], v[0:1]
	v_mov_b64_e32 v[10:11], v[0:1]
	v_mov_b64_e32 v[12:13], v[0:1]
	v_mov_b64_e32 v[14:15], v[0:1]
	v_mov_b64_e32 v[16:17], v[0:1]
	v_mov_b64_e32 v[18:19], v[0:1]
	v_mov_b64_e32 v[20:21], v[0:1]
	v_mov_b64_e32 v[22:23], v[0:1]
	v_mov_b64_e32 v[24:25], v[0:1]
	v_mov_b64_e32 v[26:27], v[0:1]
	v_mov_b64_e32 v[28:29], v[0:1]
	v_mov_b64_e32 v[30:31], v[0:1]
	v_mov_b64_e32 v[32:33], v[0:1]
	v_mov_b64_e32 v[34:35], v[0:1]
	v_mov_b64_e32 v[36:37], v[0:1]
	v_mov_b64_e32 v[38:39], v[0:1]
	v_mov_b64_e32 v[40:41], v[0:1]
	v_mov_b64_e32 v[42:43], v[0:1]
	v_mov_b64_e32 v[44:45], v[0:1]
	v_mov_b64_e32 v[46:47], v[0:1]
	v_mov_b64_e32 v[48:49], v[0:1]
	v_mov_b64_e32 v[50:51], v[0:1]
	v_mov_b64_e32 v[52:53], v[0:1]
	v_mov_b64_e32 v[54:55], v[0:1]
	v_mov_b64_e32 v[56:57], v[0:1]
	v_mov_b64_e32 v[58:59], v[0:1]
	v_mov_b64_e32 v[60:61], v[0:1]
	v_mov_b64_e32 v[62:63], v[0:1]
	v_mov_b64_e32 v[64:65], v[0:1]
	v_mov_b64_e32 v[66:67], v[0:1]
	v_mov_b64_e32 v[68:69], v[0:1]
	v_mov_b64_e32 v[70:71], v[0:1]
	v_mov_b64_e32 v[72:73], v[0:1]
	v_mov_b64_e32 v[74:75], v[0:1]
	v_mov_b64_e32 v[76:77], v[0:1]
	v_mov_b64_e32 v[78:79], v[0:1]
	v_mov_b64_e32 v[80:81], v[0:1]
	v_mov_b64_e32 v[82:83], v[0:1]
	v_mov_b64_e32 v[84:85], v[0:1]
	v_mov_b64_e32 v[86:87], v[0:1]
	v_mov_b64_e32 v[88:89], v[0:1]
	v_mov_b64_e32 v[90:91], v[0:1]
	v_mov_b64_e32 v[92:93], v[0:1]
	v_mov_b64_e32 v[94:95], v[0:1]
	v_mov_b64_e32 v[96:97], v[0:1]
	v_mov_b64_e32 v[98:99], v[0:1]
	v_mov_b64_e32 v[100:101], v[0:1]
	v_mov_b64_e32 v[102:103], v[0:1]
	v_mov_b64_e32 v[104:105], v[0:1]
	v_mov_b64_e32 v[106:107], v[0:1]
	v_mov_b64_e32 v[108:109], v[0:1]
	v_mov_b64_e32 v[110:111], v[0:1]
	v_mov_b64_e32 v[112:113], v[0:1]
	v_mov_b64_e32 v[114:115], v[0:1]
	v_mov_b64_e32 v[116:117], v[0:1]
	v_mov_b64_e32 v[118:119], v[0:1]
	v_mov_b64_e32 v[120:121], v[0:1]
	v_mov_b64_e32 v[122:123], v[0:1]
	v_mov_b64_e32 v[124:125], v[0:1]
	v_mov_b64_e32 v[126:127], v[0:1]
